# P2b dynamic queue: memory-attention units interleaved 1:3 with sb/diff units after the first 256 pops (instead of all at the end); on top of v58
# speedup vs baseline: 1.0091x; 1.0091x over previous
.LBB0_349:
	v_readlane_b32 s0, v255, 16
	s_waitcnt lgkmcnt(0)
	s_barrier
	v_mov_b32_e32 v0, s0
	ds_read_b32 v0, v0
	s_movk_i32 s0, 0x4ff
	s_waitcnt lgkmcnt(0)
	s_barrier
	v_cmp_lt_u32_e32 vcc, s0, v0
	v_readfirstlane_b32 s16, v0
	s_mov_b64 s[0:1], -1
	s_cbranch_vccnz .LBB0_342
	s_cmpk_lt_u32 s16, 0x100
	s_cbranch_scc1 .Lq_mix_done
	s_addk_i32 s16, 0xff00
	s_lshr_b32 s5, s16, 2
	s_and_b32 s4, s16, 3
	s_cmp_eq_u32 s4, 3
	s_cbranch_scc1 .Lq_mix_mem
	s_mul_i32 s5, s5, 3
	s_add_i32 s16, s5, s4
	s_addk_i32 s16, 0x100
	s_branch .Lq_mix_done
.Lq_mix_mem:
	s_add_i32 s16, s5, 0x400
